# E phases: 8-byte bf16 row loads without the nt cache policy (default policy)
# speedup vs baseline: 1.0106x; 1.0106x over previous
.LBB0_412:
	s_add_i32 s10, s8, 0xffff8000
	s_ashr_i32 s9, s8, 31
	s_cmp_lt_i32 s8, 0x8000
	s_cselect_b32 s11, s9, 0
	s_cselect_b32 s10, s8, s10
	s_cselect_b32 s28, s37, s41
	s_cselect_b32 s29, s36, s40
	s_lshl_b64 s[10:11], s[10:11], 12
	s_add_u32 s10, s29, s10
	s_addc_u32 s11, s28, s11
	global_load_dwordx4 v[126:129], v142, s[10:11] nt
	global_load_dwordx4 v[58:61], v142, s[10:11] offset:1024 nt
	global_load_dwordx4 v[54:57], v142, s[10:11] offset:2048 nt
	global_load_dwordx4 v[50:53], v142, s[10:11] offset:3072 nt
	s_cmpk_gt_i32 s8, 0x7fff
	s_cbranch_scc1 .LBB0_414
	s_lshl_b64 s[8:9], s[8:9], 11
	s_add_u32 s8, s2, s8
	s_addc_u32 s9, s3, s9
	v_lshlrev_b32_e32 v34, 1, v62
	global_load_dwordx2 v[170:171], v34, s[8:9]
	global_load_dwordx2 v[134:135], v34, s[8:9] offset:512
	global_load_dwordx2 v[132:133], v34, s[8:9] offset:1024
	global_load_dwordx2 v[130:131], v34, s[8:9] offset:1536

.LBB0_420:
	s_add_i32 s10, s8, 0xffff8000
	s_ashr_i32 s9, s8, 31
	s_cmp_lt_i32 s8, 0x8000
	s_cselect_b32 s11, s9, 0
	s_cselect_b32 s10, s8, s10
	s_cselect_b32 s28, s37, s41
	s_cselect_b32 s29, s36, s40
	s_lshl_b64 s[10:11], s[10:11], 12
	s_add_u32 s10, s29, s10
	s_addc_u32 s11, s28, s11
	global_load_dwordx4 v[34:37], v142, s[10:11] nt
	global_load_dwordx4 v[38:41], v142, s[10:11] offset:1024 nt
	global_load_dwordx4 v[42:45], v142, s[10:11] offset:2048 nt
	global_load_dwordx4 v[46:49], v142, s[10:11] offset:3072 nt
	s_cmpk_gt_i32 s8, 0x7fff
	s_cbranch_scc1 .LBB0_422
	s_lshl_b64 s[8:9], s[8:9], 11
	s_add_u32 s8, s2, s8
	s_addc_u32 s9, s3, s9
	v_lshlrev_b32_e32 v63, 1, v62
	global_load_dwordx2 v[144:145], v63, s[8:9]
	global_load_dwordx2 v[146:147], v63, s[8:9] offset:512
	global_load_dwordx2 v[148:149], v63, s[8:9] offset:1024
	global_load_dwordx2 v[150:151], v63, s[8:9] offset:1536

; DI void phase_e(const Ctx& C, int nslab, int has_post, int pl, int ps, float pw, int has_pre, int ql, int qs, int nrows,
;                 const GAS float* xsrc, const GAS float* csrc, GAS float* xdst, GAS float* cdst, bool xs16, bool xd16) {
;     ...
;         for (int j = 0; j < 4; ++j) { v[j] = vN[j]; yw[j] = yN[j]; vN[j] = vM[j]; yN[j] = yM[j]; }
;         if (i + 16 < total) E_LOAD(i + 16, vM, yM);
.LBB0_425:
	s_cmp_ge_i32 s43, s27
	s_cbranch_scc1 .LBB0_428
	s_add_i32 s1, s42, s43
	s_add_i32 s0, s39, s43
	s_add_i32 s1, s1, 0x8000
	s_cmp_lt_i32 s43, s26
	s_cselect_b32 s0, s0, s1
	s_add_i32 s2, s0, 0xffff8000
	s_ashr_i32 s1, s0, 31
	v_readlane_b32 s80, v237, 22
	s_cmp_lt_i32 s0, 0x8000
	v_readlane_b32 s81, v237, 23
	v_readlane_b32 s84, v237, 26
	v_readlane_b32 s85, v237, 27
	s_cselect_b32 s3, s1, 0
	s_cselect_b32 s2, s0, s2
	s_mov_b64 s[36:37], s[80:81]
	s_mov_b64 s[40:41], s[84:85]
	s_cselect_b32 s6, s37, s41
	s_cselect_b32 s12, s36, s40
	s_lshl_b64 s[2:3], s[2:3], 12
	s_add_u32 s2, s12, s2
	s_addc_u32 s3, s6, s3
	global_load_dwordx4 v[122:125], v142, s[2:3] nt
	global_load_dwordx4 v[118:121], v142, s[2:3] offset:1024 nt
	global_load_dwordx4 v[114:117], v142, s[2:3] offset:2048 nt
	global_load_dwordx4 v[110:113], v142, s[2:3] offset:3072 nt
	s_cmpk_gt_i32 s0, 0x7fff
	v_mov_b64_e32 v[162:163], v[144:145]
	v_mov_b64_e32 v[164:165], v[146:147]
	v_mov_b64_e32 v[166:167], v[148:149]
	v_mov_b64_e32 v[168:169], v[150:151]
	v_readlane_b32 s82, v237, 24
	v_readlane_b32 s83, v237, 25
	v_readlane_b32 s86, v237, 28
	v_readlane_b32 s87, v237, 29
	v_readlane_b32 s88, v237, 30
	v_readlane_b32 s89, v237, 31
	v_readlane_b32 s90, v237, 32
	v_readlane_b32 s91, v237, 33
	v_readlane_b32 s92, v237, 34
	v_readlane_b32 s93, v237, 35
	v_readlane_b32 s94, v237, 36
	v_readlane_b32 s95, v237, 37
	s_cbranch_scc1 .LBB0_428
	s_lshl_b64 s[0:1], s[0:1], 11
	v_lshl_add_u64 v[136:137], v[152:153], 0, s[0:1]
	global_load_dwordx2 v[162:163], v[136:137], off
	global_load_dwordx2 v[164:165], v[136:137], off offset:512
	global_load_dwordx2 v[166:167], v[136:137], off offset:1024
	global_load_dwordx2 v[168:169], v[136:137], off offset:1536

; DI void phase_e(const Ctx& C, int nslab, int has_post, int pl, int ps, float pw, int has_pre, int ql, int qs, int nrows,
;                 const GAS float* xsrc, const GAS float* csrc, GAS float* xdst, GAS float* cdst, bool xs16, bool xd16) {
;     ...
;         for (int j = 0; j < 4; ++j) { v[j] = vN[j]; yw[j] = yN[j]; vN[j] = vM[j]; yN[j] = yM[j]; }
;         if (i + 16 < total) E_LOAD(i + 16, vM, yM);
.Lrow1_425:
	s_cmp_ge_i32 s43, s27
	s_cbranch_scc1 .Lrow1_428
	s_add_i32 s1, s42, s43
	s_add_i32 s0, s39, s43
	s_add_i32 s1, s1, 0x8000
	s_cmp_lt_i32 s43, s26
	s_cselect_b32 s0, s0, s1
	s_add_i32 s2, s0, 0xffff8000
	s_ashr_i32 s1, s0, 31
	v_readlane_b32 s80, v237, 22
	s_cmp_lt_i32 s0, 0x8000
	v_readlane_b32 s81, v237, 23
	v_readlane_b32 s84, v237, 26
	v_readlane_b32 s85, v237, 27
	s_cselect_b32 s3, s1, 0
	s_cselect_b32 s2, s0, s2
	s_mov_b64 s[36:37], s[80:81]
	s_mov_b64 s[40:41], s[84:85]
	s_cselect_b32 s6, s37, s41
	s_cselect_b32 s12, s36, s40
	s_lshl_b64 s[2:3], s[2:3], 12
	s_add_u32 s2, s12, s2
	s_addc_u32 s3, s6, s3
	global_load_dwordx4 v[126:129], v142, s[2:3] nt
	global_load_dwordx4 v[58:61], v142, s[2:3] offset:1024 nt
	global_load_dwordx4 v[54:57], v142, s[2:3] offset:2048 nt
	global_load_dwordx4 v[50:53], v142, s[2:3] offset:3072 nt
	s_cmpk_gt_i32 s0, 0x7fff
	v_mov_b64_e32 v[162:163], v[144:145]
	v_mov_b64_e32 v[164:165], v[146:147]
	v_mov_b64_e32 v[166:167], v[148:149]
	v_mov_b64_e32 v[168:169], v[150:151]
	v_readlane_b32 s82, v237, 24
	v_readlane_b32 s83, v237, 25
	v_readlane_b32 s86, v237, 28
	v_readlane_b32 s87, v237, 29
	v_readlane_b32 s88, v237, 30
	v_readlane_b32 s89, v237, 31
	v_readlane_b32 s90, v237, 32
	v_readlane_b32 s91, v237, 33
	v_readlane_b32 s92, v237, 34
	v_readlane_b32 s93, v237, 35
	v_readlane_b32 s94, v237, 36
	v_readlane_b32 s95, v237, 37
	s_cbranch_scc1 .Lrow1_428
	s_lshl_b64 s[0:1], s[0:1], 11
	v_lshl_add_u64 v[136:137], v[152:153], 0, s[0:1]
	global_load_dwordx2 v[162:163], v[136:137], off
	global_load_dwordx2 v[164:165], v[136:137], off offset:512
	global_load_dwordx2 v[166:167], v[136:137], off offset:1024
	global_load_dwordx2 v[168:169], v[136:137], off offset:1536

; DI void phase_e(const Ctx& C, int nslab, int has_post, int pl, int ps, float pw, int has_pre, int ql, int qs, int nrows,
;                 const GAS float* xsrc, const GAS float* csrc, GAS float* xdst, GAS float* cdst, bool xs16, bool xd16) {
;     ...
;         for (int j = 0; j < 4; ++j) { v[j] = vN[j]; yw[j] = yN[j]; vN[j] = vM[j]; yN[j] = yM[j]; }
;         if (i + 16 < total) E_LOAD(i + 16, vM, yM);
.Lrow2_425:
	s_cmp_ge_i32 s43, s27
	s_cbranch_scc1 .Lrow2_428
	s_add_i32 s1, s42, s43
	s_add_i32 s0, s39, s43
	s_add_i32 s1, s1, 0x8000
	s_cmp_lt_i32 s43, s26
	s_cselect_b32 s0, s0, s1
	s_add_i32 s2, s0, 0xffff8000
	s_ashr_i32 s1, s0, 31
	v_readlane_b32 s80, v237, 22
	s_cmp_lt_i32 s0, 0x8000
	v_readlane_b32 s81, v237, 23
	v_readlane_b32 s84, v237, 26
	v_readlane_b32 s85, v237, 27
	s_cselect_b32 s3, s1, 0
	s_cselect_b32 s2, s0, s2
	s_mov_b64 s[36:37], s[80:81]
	s_mov_b64 s[40:41], s[84:85]
	s_cselect_b32 s6, s37, s41
	s_cselect_b32 s12, s36, s40
	s_lshl_b64 s[2:3], s[2:3], 12
	s_add_u32 s2, s12, s2
	s_addc_u32 s3, s6, s3
	global_load_dwordx4 v[34:37], v142, s[2:3] nt
	global_load_dwordx4 v[38:41], v142, s[2:3] offset:1024 nt
	global_load_dwordx4 v[42:45], v142, s[2:3] offset:2048 nt
	global_load_dwordx4 v[46:49], v142, s[2:3] offset:3072 nt
	s_cmpk_gt_i32 s0, 0x7fff
	v_mov_b64_e32 v[162:163], v[144:145]
	v_mov_b64_e32 v[164:165], v[146:147]
	v_mov_b64_e32 v[166:167], v[148:149]
	v_mov_b64_e32 v[168:169], v[150:151]
	v_readlane_b32 s82, v237, 24
	v_readlane_b32 s83, v237, 25
	v_readlane_b32 s86, v237, 28
	v_readlane_b32 s87, v237, 29
	v_readlane_b32 s88, v237, 30
	v_readlane_b32 s89, v237, 31
	v_readlane_b32 s90, v237, 32
	v_readlane_b32 s91, v237, 33
	v_readlane_b32 s92, v237, 34
	v_readlane_b32 s93, v237, 35
	v_readlane_b32 s94, v237, 36
	v_readlane_b32 s95, v237, 37
	s_cbranch_scc1 .Lrow2_428
	s_lshl_b64 s[0:1], s[0:1], 11
	v_lshl_add_u64 v[136:137], v[152:153], 0, s[0:1]
	global_load_dwordx2 v[162:163], v[136:137], off
	global_load_dwordx2 v[164:165], v[136:137], off offset:512
	global_load_dwordx2 v[166:167], v[136:137], off offset:1024
	global_load_dwordx2 v[168:169], v[136:137], off offset:1536

.LBB0_928:
.LBB0_929:
	s_ashr_i32 s11, s10, 31
	s_lshl_b64 s[14:15], s[10:11], 11
	s_add_u32 s14, s2, s14
	s_addc_u32 s15, s3, s15
	s_waitcnt vmcnt(8)
	v_lshlrev_b32_e32 v42, 1, v62
	global_load_dwordx2 v[34:35], v42, s[14:15]
	global_load_dwordx2 v[36:37], v42, s[14:15] offset:512
	global_load_dwordx2 v[38:39], v42, s[14:15] offset:1024
	global_load_dwordx2 v[40:41], v42, s[14:15] offset:1536
	s_waitcnt vmcnt(3)
	v_lshlrev_b32_e32 v78, 16, v34
	v_and_b32_e32 v79, 0xffff0000, v34
	v_lshlrev_b32_e32 v80, 16, v35
	v_and_b32_e32 v81, 0xffff0000, v35
	s_waitcnt vmcnt(2)
	v_lshlrev_b32_e32 v58, 16, v36
	v_and_b32_e32 v59, 0xffff0000, v36
	v_lshlrev_b32_e32 v60, 16, v37
	v_and_b32_e32 v61, 0xffff0000, v37
	s_waitcnt vmcnt(1)
	v_lshlrev_b32_e32 v54, 16, v38
	v_and_b32_e32 v55, 0xffff0000, v38
	v_lshlrev_b32_e32 v56, 16, v39
	v_and_b32_e32 v57, 0xffff0000, v39
	s_waitcnt vmcnt(0)
	v_lshlrev_b32_e32 v46, 16, v40
	v_and_b32_e32 v47, 0xffff0000, v40
	v_lshlrev_b32_e32 v48, 16, v41
	v_and_b32_e32 v49, 0xffff0000, v41
.LBB0_930:
	s_andn2_b64 vcc, exec, s[12:13]
	s_cbranch_vccnz .LBB0_932
	s_ashr_i32 s11, s10, 31
	s_lshl_b64 s[10:11], s[10:11], 11
	s_add_u32 s10, s6, s10
	s_addc_u32 s11, s7, s11
	v_lshlrev_b32_e32 v34, 1, v62
	global_load_dwordx2 v[136:137], v34, s[10:11]
	global_load_dwordx2 v[134:135], v34, s[10:11] offset:512
	global_load_dwordx2 v[132:133], v34, s[10:11] offset:1024
	global_load_dwordx2 v[130:131], v34, s[10:11] offset:1536
	s_add_i32 s11, s22, 8
	s_cmp_ge_i32 s11, s17
	s_cbranch_scc0 .LBB0_933
	s_branch .LBB0_923

.LBB0_939:
.LBB0_940:
	s_ashr_i32 s11, s10, 31
	s_lshl_b64 s[14:15], s[10:11], 11
	s_add_u32 s14, s2, s14
	s_addc_u32 s15, s3, s15
	s_waitcnt vmcnt(3)
	v_lshlrev_b32_e32 v34, 1, v62
	global_load_dwordx2 v[36:37], v34, s[14:15]
	global_load_dwordx2 v[40:41], v34, s[14:15] offset:512
	global_load_dwordx2 v[44:45], v34, s[14:15] offset:1024
	global_load_dwordx2 v[52:53], v34, s[14:15] offset:1536
	s_waitcnt vmcnt(3)
	v_lshlrev_b32_e32 v34, 16, v36
	v_and_b32_e32 v35, 0xffff0000, v36
	v_lshlrev_b32_e32 v36, 16, v37
	v_and_b32_e32 v37, 0xffff0000, v37
	s_waitcnt vmcnt(2)
	v_lshlrev_b32_e32 v38, 16, v40
	v_and_b32_e32 v39, 0xffff0000, v40
	v_lshlrev_b32_e32 v40, 16, v41
	v_and_b32_e32 v41, 0xffff0000, v41
	s_waitcnt vmcnt(1)
	v_lshlrev_b32_e32 v42, 16, v44
	v_and_b32_e32 v43, 0xffff0000, v44
	v_lshlrev_b32_e32 v44, 16, v45
	v_and_b32_e32 v45, 0xffff0000, v45
	s_waitcnt vmcnt(0)
	v_lshlrev_b32_e32 v50, 16, v52
	v_and_b32_e32 v51, 0xffff0000, v52
	v_lshlrev_b32_e32 v52, 16, v53
	v_and_b32_e32 v53, 0xffff0000, v53
.LBB0_941:
	s_andn2_b64 vcc, exec, s[12:13]
	s_cbranch_vccnz .LBB0_943
	s_ashr_i32 s11, s10, 31
	s_lshl_b64 s[10:11], s[10:11], 11
	s_add_u32 s10, s6, s10
	s_addc_u32 s11, s7, s11
	v_lshlrev_b32_e32 v63, 1, v62
	global_load_dwordx2 v[144:145], v63, s[10:11]
	global_load_dwordx2 v[146:147], v63, s[10:11] offset:512
	global_load_dwordx2 v[148:149], v63, s[10:11] offset:1024
	global_load_dwordx2 v[150:151], v63, s[10:11] offset:1536
	s_andn2_b64 vcc, exec, s[8:9]
	s_cbranch_vccz .LBB0_944
	s_branch .LBB0_975

.LBB0_949:
	s_andn2_b64 vcc, exec, s[10:11]
	s_cbranch_vccnz .LBB0_951
	s_ashr_i32 s1, s0, 31
	s_lshl_b64 s[10:11], s[0:1], 11
	s_waitcnt vmcnt(3)
	v_lshl_add_u64 v[114:115], v[152:153], 0, s[10:11]
	global_load_dwordx2 v[116:117], v[114:115], off
	global_load_dwordx2 v[120:121], v[114:115], off offset:512
	global_load_dwordx2 v[124:125], v[114:115], off offset:1024
	global_load_dwordx2 v[128:129], v[114:115], off offset:1536
	s_mov_b64 s[98:99], -1
.LBB0_951:
	s_andn2_b64 vcc, exec, s[2:3]
	v_mov_b64_e32 v[162:163], v[144:145]
	v_mov_b64_e32 v[164:165], v[146:147]
	v_mov_b64_e32 v[166:167], v[148:149]
	v_mov_b64_e32 v[168:169], v[150:151]
	s_cbranch_vccnz .LBB0_953
	s_ashr_i32 s1, s0, 31
	s_lshl_b64 s[0:1], s[0:1], 11
	v_lshl_add_u64 v[138:139], v[154:155], 0, s[0:1]
	global_load_dwordx2 v[162:163], v[138:139], off
	global_load_dwordx2 v[164:165], v[138:139], off offset:512
	global_load_dwordx2 v[166:167], v[138:139], off offset:1024
	global_load_dwordx2 v[168:169], v[138:139], off offset:1536

.Lrow1_949:
	s_andn2_b64 vcc, exec, s[10:11]
	s_cbranch_vccnz .Lrow1_951
	s_ashr_i32 s1, s0, 31
	s_lshl_b64 s[10:11], s[0:1], 11
	s_waitcnt vmcnt(3)
	v_lshl_add_u64 v[78:79], v[152:153], 0, s[10:11]
	global_load_dwordx2 v[80:81], v[78:79], off
	global_load_dwordx2 v[60:61], v[78:79], off offset:512
	global_load_dwordx2 v[56:57], v[78:79], off offset:1024
	global_load_dwordx2 v[48:49], v[78:79], off offset:1536
	s_mov_b64 s[98:99], -1

.Lrow2_949:
	s_andn2_b64 vcc, exec, s[10:11]
	s_cbranch_vccnz .Lrow2_951
	s_ashr_i32 s1, s0, 31
	s_lshl_b64 s[10:11], s[0:1], 11
	s_waitcnt vmcnt(3)
	v_lshl_add_u64 v[34:35], v[152:153], 0, s[10:11]
	global_load_dwordx2 v[36:37], v[34:35], off
	global_load_dwordx2 v[40:41], v[34:35], off offset:512
	global_load_dwordx2 v[44:45], v[34:35], off offset:1024
	global_load_dwordx2 v[52:53], v[34:35], off offset:1536
	s_mov_b64 s[98:99], -1

.LBB0_1195:
.LBB0_1196:
	s_ashr_i32 s11, s10, 31
	s_lshl_b64 s[14:15], s[10:11], 11
	s_add_u32 s14, s2, s14
	s_addc_u32 s15, s3, s15
	s_waitcnt vmcnt(8)
	v_lshlrev_b32_e32 v42, 1, v62
	global_load_dwordx2 v[34:35], v42, s[14:15]
	global_load_dwordx2 v[36:37], v42, s[14:15] offset:512
	global_load_dwordx2 v[38:39], v42, s[14:15] offset:1024
	global_load_dwordx2 v[40:41], v42, s[14:15] offset:1536
	s_waitcnt vmcnt(3)
	v_lshlrev_b32_e32 v98, 16, v34
	v_and_b32_e32 v99, 0xffff0000, v34
	v_lshlrev_b32_e32 v100, 16, v35
	v_and_b32_e32 v101, 0xffff0000, v35
	s_waitcnt vmcnt(2)
	v_lshlrev_b32_e32 v58, 16, v36
	v_and_b32_e32 v59, 0xffff0000, v36
	v_lshlrev_b32_e32 v60, 16, v37
	v_and_b32_e32 v61, 0xffff0000, v37
	s_waitcnt vmcnt(1)
	v_lshlrev_b32_e32 v54, 16, v38
	v_and_b32_e32 v55, 0xffff0000, v38
	v_lshlrev_b32_e32 v56, 16, v39
	v_and_b32_e32 v57, 0xffff0000, v39
	s_waitcnt vmcnt(0)
	v_lshlrev_b32_e32 v46, 16, v40
	v_and_b32_e32 v47, 0xffff0000, v40
	v_lshlrev_b32_e32 v48, 16, v41
	v_and_b32_e32 v49, 0xffff0000, v41
.LBB0_1197:
	s_andn2_b64 vcc, exec, s[12:13]
	s_cbranch_vccnz .LBB0_1199
	s_ashr_i32 s11, s10, 31
	s_lshl_b64 s[10:11], s[10:11], 11
	s_add_u32 s10, s6, s10
	s_addc_u32 s11, s7, s11
	v_lshlrev_b32_e32 v34, 1, v62
	global_load_dwordx2 v[170:171], v34, s[10:11]
	global_load_dwordx2 v[134:135], v34, s[10:11] offset:512
	global_load_dwordx2 v[132:133], v34, s[10:11] offset:1024
	global_load_dwordx2 v[130:131], v34, s[10:11] offset:1536
	s_add_i32 s11, s21, 8
	s_cmp_ge_i32 s11, s17
	s_cbranch_scc0 .LBB0_1200
	s_branch .LBB0_1190

.LBB0_1218:
	s_andn2_b64 vcc, exec, s[2:3]
	v_mov_b64_e32 v[162:163], v[144:145]
	v_mov_b64_e32 v[164:165], v[146:147]
	v_mov_b64_e32 v[166:167], v[148:149]
	v_mov_b64_e32 v[168:169], v[150:151]
	s_cbranch_vccnz .LBB0_1220
	s_ashr_i32 s1, s0, 31
	s_lshl_b64 s[0:1], s[0:1], 11
	v_lshl_add_u64 v[136:137], v[154:155], 0, s[0:1]
	global_load_dwordx2 v[162:163], v[136:137], off
	global_load_dwordx2 v[164:165], v[136:137], off offset:512
	global_load_dwordx2 v[166:167], v[136:137], off offset:1024
	global_load_dwordx2 v[168:169], v[136:137], off offset:1536

.Lrow1_1216:
	s_andn2_b64 vcc, exec, s[10:11]
	s_cbranch_vccnz .Lrow1_1218
	s_ashr_i32 s1, s0, 31
	s_lshl_b64 s[10:11], s[0:1], 11
	s_waitcnt vmcnt(3)
	v_lshl_add_u64 v[98:99], v[152:153], 0, s[10:11]
	global_load_dwordx2 v[100:101], v[98:99], off
	global_load_dwordx2 v[60:61], v[98:99], off offset:512
	global_load_dwordx2 v[56:57], v[98:99], off offset:1024
	global_load_dwordx2 v[48:49], v[98:99], off offset:1536
	s_mov_b64 s[98:99], -1

.LBB0_1465:
	s_andn2_b64 vcc, exec, s[12:13]
	s_cbranch_vccnz .LBB0_1467
	s_ashr_i32 s11, s10, 31
	s_lshl_b64 s[10:11], s[10:11], 11
	s_add_u32 s10, s6, s10
	s_addc_u32 s11, s7, s11
	v_lshlrev_b32_e32 v34, 1, v62
	global_load_dwordx2 v[170:171], v34, s[10:11]
	global_load_dwordx2 v[134:135], v34, s[10:11] offset:512
	global_load_dwordx2 v[132:133], v34, s[10:11] offset:1024
	global_load_dwordx2 v[130:131], v34, s[10:11] offset:1536
	s_add_i32 s11, s22, 8
	s_cmp_ge_i32 s11, s17
	s_cbranch_scc0 .LBB0_1468
	s_branch .LBB0_1458

.LBB0_2200:
.LBB0_2201:
	s_ashr_i32 s13, s12, 31
	s_lshl_b64 s[10:11], s[12:13], 11
	s_add_u32 s12, s2, s10
	s_addc_u32 s13, s3, s11
	s_waitcnt vmcnt(8)
	v_lshlrev_b32_e32 v42, 1, v66
	global_load_dwordx2 v[34:35], v42, s[12:13]
	global_load_dwordx2 v[36:37], v42, s[12:13] offset:512
	global_load_dwordx2 v[38:39], v42, s[12:13] offset:1024
	global_load_dwordx2 v[40:41], v42, s[12:13] offset:1536
	s_waitcnt vmcnt(3)
	v_lshlrev_b32_e32 v62, 16, v34
	v_and_b32_e32 v63, 0xffff0000, v34
	v_lshlrev_b32_e32 v64, 16, v35
	v_and_b32_e32 v65, 0xffff0000, v35
	s_waitcnt vmcnt(2)
	v_lshlrev_b32_e32 v58, 16, v36
	v_and_b32_e32 v59, 0xffff0000, v36
	v_lshlrev_b32_e32 v60, 16, v37
	v_and_b32_e32 v61, 0xffff0000, v37
	s_waitcnt vmcnt(1)
	v_lshlrev_b32_e32 v54, 16, v38
	v_and_b32_e32 v55, 0xffff0000, v38
	v_lshlrev_b32_e32 v56, 16, v39
	v_and_b32_e32 v57, 0xffff0000, v39
	s_waitcnt vmcnt(0)
	v_lshlrev_b32_e32 v50, 16, v40
	v_and_b32_e32 v51, 0xffff0000, v40
	v_lshlrev_b32_e32 v52, 16, v41
	v_and_b32_e32 v53, 0xffff0000, v41
.LBB0_2202:
	s_add_u32 s10, s6, s10
	s_addc_u32 s11, s7, s11
	v_lshlrev_b32_e32 v34, 1, v66
	global_load_dwordx2 v[136:137], v34, s[10:11]
	global_load_dwordx2 v[134:135], v34, s[10:11] offset:512
	global_load_dwordx2 v[132:133], v34, s[10:11] offset:1024
	global_load_dwordx2 v[130:131], v34, s[10:11] offset:1536
	s_add_i32 s10, s16, 8
	s_cmp_ge_i32 s10, s17
	s_cbranch_scc1 .LBB0_2199

.LBB0_2205:
.LBB0_2206:
	s_ashr_i32 s13, s12, 31
	s_lshl_b64 s[10:11], s[12:13], 11
	s_add_u32 s12, s2, s10
	s_addc_u32 s13, s3, s11
	s_waitcnt vmcnt(3)
	v_lshlrev_b32_e32 v34, 1, v66
	global_load_dwordx2 v[36:37], v34, s[12:13]
	global_load_dwordx2 v[40:41], v34, s[12:13] offset:512
	global_load_dwordx2 v[44:45], v34, s[12:13] offset:1024
	global_load_dwordx2 v[48:49], v34, s[12:13] offset:1536
	s_waitcnt vmcnt(3)
	v_lshlrev_b32_e32 v34, 16, v36
	v_and_b32_e32 v35, 0xffff0000, v36
	v_lshlrev_b32_e32 v36, 16, v37
	v_and_b32_e32 v37, 0xffff0000, v37
	s_waitcnt vmcnt(2)
	v_lshlrev_b32_e32 v38, 16, v40
	v_and_b32_e32 v39, 0xffff0000, v40
	v_lshlrev_b32_e32 v40, 16, v41
	v_and_b32_e32 v41, 0xffff0000, v41
	s_waitcnt vmcnt(1)
	v_lshlrev_b32_e32 v42, 16, v44
	v_and_b32_e32 v43, 0xffff0000, v44
	v_lshlrev_b32_e32 v44, 16, v45
	v_and_b32_e32 v45, 0xffff0000, v45
	s_waitcnt vmcnt(0)
	v_lshlrev_b32_e32 v46, 16, v48
	v_and_b32_e32 v47, 0xffff0000, v48
	v_lshlrev_b32_e32 v48, 16, v49
	v_and_b32_e32 v49, 0xffff0000, v49
.LBB0_2207:
	s_add_u32 s10, s6, s10
	s_addc_u32 s11, s7, s11
	v_lshlrev_b32_e32 v67, 1, v66
	global_load_dwordx2 v[148:149], v67, s[10:11]
	global_load_dwordx2 v[150:151], v67, s[10:11] offset:512
	global_load_dwordx2 v[152:153], v67, s[10:11] offset:1024
	global_load_dwordx2 v[154:155], v67, s[10:11] offset:1536
	s_andn2_b64 vcc, exec, s[8:9]
	s_cbranch_vccnz .LBB0_2222

.LBB0_2213:
	s_andn2_b64 vcc, exec, s[12:13]
	s_cbranch_vccnz .LBB0_2215
	s_ashr_i32 s11, s10, 31
	s_lshl_b64 s[8:9], s[10:11], 11
	s_waitcnt vmcnt(3)
	v_lshl_add_u64 v[114:115], v[156:157], 0, s[8:9]
	global_load_dwordx2 v[116:117], v[114:115], off
	global_load_dwordx2 v[120:121], v[114:115], off offset:512
	global_load_dwordx2 v[124:125], v[114:115], off offset:1024
	global_load_dwordx2 v[128:129], v[114:115], off offset:1536
	s_mov_b64 s[98:99], -1
.LBB0_2215:
	v_lshl_add_u64 v[138:139], v[158:159], 0, s[8:9]
	global_load_dwordx2 v[166:167], v[138:139], off
	global_load_dwordx2 v[168:169], v[138:139], off offset:512
	global_load_dwordx2 v[170:171], v[138:139], off offset:1024
	global_load_dwordx2 v[172:173], v[138:139], off offset:1536

.Lrow1_2213:
	s_andn2_b64 vcc, exec, s[12:13]
	s_cbranch_vccnz .Lrow1_2215
	s_ashr_i32 s11, s10, 31
	s_lshl_b64 s[8:9], s[10:11], 11
	s_waitcnt vmcnt(3)
	v_lshl_add_u64 v[62:63], v[156:157], 0, s[8:9]
	global_load_dwordx2 v[64:65], v[62:63], off
	global_load_dwordx2 v[60:61], v[62:63], off offset:512
	global_load_dwordx2 v[56:57], v[62:63], off offset:1024
	global_load_dwordx2 v[52:53], v[62:63], off offset:1536
	s_mov_b64 s[98:99], -1

.Lrow2_2213:
	s_andn2_b64 vcc, exec, s[12:13]
	s_cbranch_vccnz .Lrow2_2215
	s_ashr_i32 s11, s10, 31
	s_lshl_b64 s[8:9], s[10:11], 11
	s_waitcnt vmcnt(3)
	v_lshl_add_u64 v[34:35], v[156:157], 0, s[8:9]
	global_load_dwordx2 v[36:37], v[34:35], off
	global_load_dwordx2 v[40:41], v[34:35], off offset:512
	global_load_dwordx2 v[44:45], v[34:35], off offset:1024
	global_load_dwordx2 v[48:49], v[34:35], off offset:1536
	s_mov_b64 s[98:99], -1

.LBB0_2435:
.LBB0_2436:
	s_ashr_i32 s11, s10, 31
	s_lshl_b64 s[8:9], s[10:11], 11
	s_add_u32 s10, s2, s8
	s_addc_u32 s11, s3, s9
	s_waitcnt vmcnt(1)
	v_lshlrev_b32_e32 v22, 1, v50
	global_load_dwordx2 v[18:19], v22, s[10:11]
	global_load_dwordx2 v[20:21], v22, s[10:11] offset:512
	global_load_dwordx2 v[24:25], v22, s[10:11] offset:1024
	global_load_dwordx2 v[34:35], v22, s[10:11] offset:1536
	s_waitcnt vmcnt(3)
	v_lshlrev_b32_e32 v30, 16, v18
	v_and_b32_e32 v31, 0xffff0000, v18
	v_lshlrev_b32_e32 v32, 16, v19
	v_and_b32_e32 v33, 0xffff0000, v19
	s_waitcnt vmcnt(2)
	v_lshlrev_b32_e32 v26, 16, v20
	v_and_b32_e32 v27, 0xffff0000, v20
	v_lshlrev_b32_e32 v28, 16, v21
	v_and_b32_e32 v29, 0xffff0000, v21
	s_waitcnt vmcnt(1)
	v_lshlrev_b32_e32 v22, 16, v24
	v_and_b32_e32 v23, 0xffff0000, v24
	v_lshlrev_b32_e32 v24, 16, v25
	v_and_b32_e32 v25, 0xffff0000, v25
	s_waitcnt vmcnt(0)
	v_lshlrev_b32_e32 v18, 16, v34
	v_and_b32_e32 v19, 0xffff0000, v34
	v_lshlrev_b32_e32 v20, 16, v35
	v_and_b32_e32 v21, 0xffff0000, v35
.LBB0_2437:
	s_add_u32 s8, s4, s8
	s_addc_u32 s9, s5, s9
	v_lshlrev_b32_e32 v34, 1, v50
	global_load_dwordx2 v[98:99], v34, s[8:9]
	global_load_dwordx2 v[90:91], v34, s[8:9] offset:512
	global_load_dwordx2 v[86:87], v34, s[8:9] offset:1024
	global_load_dwordx2 v[84:85], v34, s[8:9] offset:1536
	s_add_i32 s8, s14, 8
	s_cmp_ge_i32 s8, s15
	s_cbranch_scc1 .LBB0_2434

.LBB0_2440:
.LBB0_2441:
	s_ashr_i32 s11, s10, 31
	s_lshl_b64 s[8:9], s[10:11], 11
	s_add_u32 s10, s2, s8
	s_addc_u32 s11, s3, s9
	s_waitcnt vmcnt(3)
	v_lshlrev_b32_e32 v34, 1, v50
	global_load_dwordx2 v[36:37], v34, s[10:11]
	global_load_dwordx2 v[40:41], v34, s[10:11] offset:512
	global_load_dwordx2 v[44:45], v34, s[10:11] offset:1024
	global_load_dwordx2 v[48:49], v34, s[10:11] offset:1536
	s_waitcnt vmcnt(3)
	v_lshlrev_b32_e32 v34, 16, v36
	v_and_b32_e32 v35, 0xffff0000, v36
	v_lshlrev_b32_e32 v36, 16, v37
	v_and_b32_e32 v37, 0xffff0000, v37
	s_waitcnt vmcnt(2)
	v_lshlrev_b32_e32 v38, 16, v40
	v_and_b32_e32 v39, 0xffff0000, v40
	v_lshlrev_b32_e32 v40, 16, v41
	v_and_b32_e32 v41, 0xffff0000, v41
	s_waitcnt vmcnt(1)
	v_lshlrev_b32_e32 v42, 16, v44
	v_and_b32_e32 v43, 0xffff0000, v44
	v_lshlrev_b32_e32 v44, 16, v45
	v_and_b32_e32 v45, 0xffff0000, v45
	s_waitcnt vmcnt(0)
	v_lshlrev_b32_e32 v46, 16, v48
	v_and_b32_e32 v47, 0xffff0000, v48
	v_lshlrev_b32_e32 v48, 16, v49
	v_and_b32_e32 v49, 0xffff0000, v49
.LBB0_2442:
	s_add_u32 s8, s4, s8
	s_addc_u32 s9, s5, s9
	v_lshlrev_b32_e32 v51, 1, v50
	global_load_dwordx2 v[88:89], v51, s[8:9]
	global_load_dwordx2 v[92:93], v51, s[8:9] offset:512
	global_load_dwordx2 v[94:95], v51, s[8:9] offset:1024
	global_load_dwordx2 v[96:97], v51, s[8:9] offset:1536
	s_andn2_b64 vcc, exec, s[6:7]
	s_cbranch_vccnz .LBB0_2453

.LBB0_2448:
	s_andn2_b64 vcc, exec, s[10:11]
	s_cbranch_vccnz .LBB0_2450
	s_ashr_i32 s9, s8, 31
	s_lshl_b64 s[6:7], s[8:9], 11
	s_waitcnt vmcnt(3)
	v_lshl_add_u64 v[66:67], v[100:101], 0, s[6:7]
	global_load_dwordx2 v[68:69], v[66:67], off
	global_load_dwordx2 v[72:73], v[66:67], off offset:512
	global_load_dwordx2 v[76:77], v[66:67], off offset:1024
	global_load_dwordx2 v[80:81], v[66:67], off offset:1536
	s_mov_b64 s[98:99], -1
.LBB0_2450:
	v_lshl_add_u64 v[122:123], v[102:103], 0, s[6:7]
	global_load_dwordx2 v[106:107], v[122:123], off
	global_load_dwordx2 v[108:109], v[122:123], off offset:512
	global_load_dwordx2 v[110:111], v[122:123], off offset:1024
	global_load_dwordx2 v[112:113], v[122:123], off offset:1536

.Lrow1_2448:
	s_andn2_b64 vcc, exec, s[10:11]
	s_cbranch_vccnz .Lrow1_2450
	s_ashr_i32 s9, s8, 31
	s_lshl_b64 s[6:7], s[8:9], 11
	s_waitcnt vmcnt(3)
	v_lshl_add_u64 v[30:31], v[100:101], 0, s[6:7]
	global_load_dwordx2 v[32:33], v[30:31], off
	global_load_dwordx2 v[28:29], v[30:31], off offset:512
	global_load_dwordx2 v[24:25], v[30:31], off offset:1024
	global_load_dwordx2 v[20:21], v[30:31], off offset:1536
	s_mov_b64 s[98:99], -1
.Lrow1_2450:
	v_lshl_add_u64 v[122:123], v[102:103], 0, s[6:7]
	global_load_dwordx2 v[98:99], v[122:123], off
	global_load_dwordx2 v[90:91], v[122:123], off offset:512
	global_load_dwordx2 v[86:87], v[122:123], off offset:1024
	global_load_dwordx2 v[84:85], v[122:123], off offset:1536

.Lrow2_2448:
	s_andn2_b64 vcc, exec, s[10:11]
	s_cbranch_vccnz .Lrow2_2450
	s_ashr_i32 s9, s8, 31
	s_lshl_b64 s[6:7], s[8:9], 11
	s_waitcnt vmcnt(3)
	v_lshl_add_u64 v[34:35], v[100:101], 0, s[6:7]
	global_load_dwordx2 v[36:37], v[34:35], off
	global_load_dwordx2 v[40:41], v[34:35], off offset:512
	global_load_dwordx2 v[44:45], v[34:35], off offset:1024
	global_load_dwordx2 v[48:49], v[34:35], off offset:1536
	s_mov_b64 s[98:99], -1
.Lrow2_2450:
	v_lshl_add_u64 v[122:123], v[102:103], 0, s[6:7]
	global_load_dwordx2 v[88:89], v[122:123], off
	global_load_dwordx2 v[92:93], v[122:123], off offset:512
	global_load_dwordx2 v[94:95], v[122:123], off offset:1024
	global_load_dwordx2 v[96:97], v[122:123], off offset:1536
